# qk-norm/rope phase: next-row loads prefetched one iteration ahead, gain loads hoisted
# speedup vs baseline: 1.0252x; 1.0067x over previous
; __device__ __forceinline__ int my_tid() { int t = threadIdx.x; asm volatile("" : "+v"(t)); return t; }
; __device__ __forceinline__ void phase_qkprep(bf16_t* proj, const float* gqk  , const float2* rope) {
;     const int tid = my_tid(), lane = tid & 63, wave = tid >> 6;
;     const int gw = blockIdx.x * 8 + wave, NGW = gridDim.x * 8;
;     const int grp = lane >> 2, u = lane & 3;
;     for (int it = gw; it < TG * 2; it += NGW) {
;         const int row = it >> 1, which = it & 1, pos = row & (SEQ - 1);
;         bf16_t* p = proj + (which ? SEC(C_AK) : SEC(C_AQ)) + (size_t)row * PP + grp * 64 + 8 * u;
;         const u32x4 a = *(const u32x4*)p, b = *(const u32x4*)(p + 32);
;         float x1[8], x2[8]; unpack8(a, x1); unpack8(b, x2);
;         float ss = 0.f;
; #pragma unroll
;         for (int e = 0; e < 8; ++e) ss += x1[e] * x1[e] + x2[e] * x2[e];
;         ss += __shfl_xor(ss, 1); ss += __shfl_xor(ss, 2);
;         const float rstd = 1.0f / sqrtf(ss * (1.0f / 64.0f) + 1e-6f) * (which ? 1.0f : 0.125f * 1.4426950408889634f);
;         const float* gq = gqk + which * 64 + 8 * u;
;         const float2* cs = rope + (size_t)pos * 32 + 8 * u;
;         float o1[8], o2[8];
; #pragma unroll
;         for (int e = 0; e < 8; ++e) { const float y1 = x1[e] * rstd * gq[e], y2 = x2[e] * rstd * gq[32 + e]; const float2 t = cs[e]; o1[e] = y1 * t.x - y2 * t.y; o2[e] = y2 * t.x + y1 * t.y; }
.LBB0_307:
	v_mov_b32_e32 v2, v194
	v_readlane_b32 s0, v254, 21
	v_ashrrev_i32_e32 v0, 6, v2
	s_waitcnt vmcnt(0)
	v_add_u32_e32 v36, s0, v0
	v_cmp_gt_i32_e32 vcc, s51, v36
	s_and_saveexec_b64 s[0:1], vcc
	s_xor_b64 s[4:5], exec, s[0:1]
	s_cbranch_execz .LBB0_311
	v_lshlrev_b32_e32 v0, 3, v2
	v_and_b32_e32 v3, 64, v235
	v_and_b32_e32 v8, 24, v0
	v_xor_b32_e32 v0, 1, v235
	v_add_u32_e32 v3, 64, v3
	v_cmp_lt_i32_e32 vcc, v0, v3
	s_lshl_b32 s0, s64, 7
	s_ashr_i32 s1, s0, 31
	v_cndmask_b32_e32 v0, v235, v0, vcc
	v_lshlrev_b32_e32 v37, 2, v0
	v_xor_b32_e32 v0, 2, v235
	s_lshl_b64 s[0:1], s[0:1], 2
	v_readlane_b32 s8, v254, 47
	v_cmp_lt_i32_e32 vcc, v0, v3
	v_readlane_b32 s9, v254, 48
	s_add_u32 s0, s8, s0
	v_cndmask_b32_e32 v0, v235, v0, vcc
	s_addc_u32 s1, s9, s1
	v_lshlrev_b32_e32 v38, 2, v0
	v_lshlrev_b32_e32 v0, 2, v8
	v_lshl_add_u64 v[4:5], s[0:1], 0, v[0:1]
	v_lshlrev_b32_e32 v0, 3, v8
	v_bfe_u32 v9, v2, 6, 1
	v_lshl_add_u64 v[14:15], s[54:55], 0, v[0:1]
	v_cmp_eq_u32_e32 vcc, 0, v9
	v_bfrev_b32_e32 v0, 48
	v_mov_b32_e32 v3, 0xa000000
	v_cndmask_b32_e32 v0, v0, v3, vcc
	v_lshl_add_u64 v[6:7], s[70:71], 0, v[0:1]
	v_lshlrev_b32_e32 v0, 5, v2
	v_and_b32_e32 v0, 0x780, v0
	v_lshl_add_u64 v[2:3], v[6:7], 0, v[0:1]
	v_lshlrev_b32_e32 v0, 1, v8
	v_lshl_add_u64 v[16:17], v[2:3], 0, v[0:1]
	v_mov_b32_e32 v0, 0x3e38aa3b
	v_cndmask_b32_e32 v39, 1.0, v0, vcc
	v_lshlrev_b32_e32 v0, 8, v9
	v_lshl_add_u64 v[18:19], v[4:5], 0, v[0:1]
	s_mov_b64 s[6:7], 0
	v_readlane_b32 s10, v254, 49
	v_readlane_b32 s11, v254, 50
	v_readlane_b32 s12, v254, 51
	v_readlane_b32 s13, v254, 52
	v_readlane_b32 s14, v254, 53
	v_readlane_b32 s15, v254, 54
	v_readlane_b32 s16, v254, 55
	v_readlane_b32 s17, v254, 56
	v_readlane_b32 s18, v254, 57
	v_readlane_b32 s19, v254, 58
	v_readlane_b32 s20, v254, 59
	v_readlane_b32 s21, v254, 60
	v_readlane_b32 s22, v254, 61
	v_readlane_b32 s23, v254, 62
	v_ashrrev_i32_e32 v184, 1, v36
	v_ashrrev_i32_e32 v185, 31, v184
	v_lshlrev_b64 v[186:187], 11, v[184:185]
	v_lshl_add_u64 v[180:181], v[16:17], 0, v[186:187]
	global_load_dwordx4 v[140:143], v[180:181], off
	global_load_dwordx4 v[144:147], v[180:181], off offset:64
	v_lshlrev_b32_e32 v188, 8, v184
	v_and_b32_e32 v188, 0xfff00, v188
	v_mov_b32_e32 v189, 0
	v_lshl_add_u64 v[182:183], v[14:15], 0, v[188:189]
	global_load_dwordx4 v[148:151], v[182:183], off offset:48
	global_load_dwordx4 v[152:155], v[182:183], off offset:32
	global_load_dwordx4 v[156:159], v[182:183], off offset:16
	global_load_dwordx4 v[160:163], v[182:183], off
	global_load_dwordx4 v[164:167], v[18:19], off offset:16
	global_load_dwordx4 v[168:171], v[18:19], off
	global_load_dwordx4 v[172:175], v[18:19], off offset:144
	global_load_dwordx4 v[176:179], v[18:19], off offset:128
	s_waitcnt vmcnt(0)
.LBB0_309:
	v_mov_b32_e32 v40, v140
	v_mov_b32_e32 v41, v141
	v_mov_b32_e32 v42, v142
	v_mov_b32_e32 v43, v143
	v_mov_b32_e32 v44, v144
	v_mov_b32_e32 v45, v145
	v_mov_b32_e32 v46, v146
	v_mov_b32_e32 v47, v147
	v_mov_b32_e32 v2, v148
	v_mov_b32_e32 v3, v149
	v_mov_b32_e32 v4, v150
	v_mov_b32_e32 v5, v151
	v_mov_b32_e32 v6, v152
	v_mov_b32_e32 v7, v153
	v_mov_b32_e32 v8, v154
	v_mov_b32_e32 v9, v155
	v_mov_b32_e32 v10, v156
	v_mov_b32_e32 v11, v157
	v_mov_b32_e32 v12, v158
	v_mov_b32_e32 v13, v159
	v_mov_b32_e32 v48, v160
	v_mov_b32_e32 v49, v161
	v_mov_b32_e32 v50, v162
	v_mov_b32_e32 v51, v163
	v_mov_b32_e32 v52, v164
	v_mov_b32_e32 v53, v165
	v_mov_b32_e32 v54, v166
	v_mov_b32_e32 v55, v167
	v_mov_b32_e32 v56, v168
	v_mov_b32_e32 v57, v169
	v_mov_b32_e32 v58, v170
	v_mov_b32_e32 v59, v171
	v_mov_b32_e32 v60, v172
	v_mov_b32_e32 v61, v173
	v_mov_b32_e32 v62, v174
	v_mov_b32_e32 v63, v175
	v_mov_b32_e32 v64, v176
	v_mov_b32_e32 v65, v177
	v_mov_b32_e32 v66, v178
	v_mov_b32_e32 v67, v179
	v_mov_b32_e32 v20, v180
	v_mov_b32_e32 v21, v181
	v_add_u32_e32 v36, s52, v36
	v_ashrrev_i32_e32 v184, 1, v36
	v_ashrrev_i32_e32 v185, 31, v184
	v_lshlrev_b64 v[186:187], 11, v[184:185]
	v_lshl_add_u64 v[180:181], v[16:17], 0, v[186:187]
	global_load_dwordx4 v[140:143], v[180:181], off
	global_load_dwordx4 v[144:147], v[180:181], off offset:64
	v_lshlrev_b32_e32 v188, 8, v184
	v_and_b32_e32 v188, 0xfff00, v188
	v_mov_b32_e32 v189, 0
	v_lshl_add_u64 v[182:183], v[14:15], 0, v[188:189]
	global_load_dwordx4 v[148:151], v[182:183], off offset:48
	global_load_dwordx4 v[152:155], v[182:183], off offset:32
	global_load_dwordx4 v[156:159], v[182:183], off offset:16
	global_load_dwordx4 v[160:163], v[182:183], off
	v_and_b32_e32 v25, 0xffff0000, v43
	v_lshlrev_b32_e32 v24, 16, v47
	v_lshlrev_b32_e32 v26, 16, v43
	v_and_b32_e32 v27, 0xffff0000, v47
	v_pk_mul_f32 v[30:31], v[24:25], v[24:25]
	v_lshlrev_b32_e32 v76, 16, v44
	v_and_b32_e32 v77, 0xffff0000, v40
	v_pk_fma_f32 v[70:71], v[26:27], v[26:27], v[30:31]
	v_lshlrev_b32_e32 v30, 16, v46
	v_and_b32_e32 v35, 0xffff0000, v46
	v_lshlrev_b32_e32 v46, 16, v45
	v_and_b32_e32 v47, 0xffff0000, v41
	v_lshlrev_b32_e32 v72, 16, v41
	v_and_b32_e32 v73, 0xffff0000, v45
	v_lshlrev_b32_e32 v40, 16, v40
	v_and_b32_e32 v41, 0xffff0000, v44
	v_pk_mul_f32 v[44:45], v[76:77], v[76:77]
	v_pk_mul_f32 v[74:75], v[46:47], v[46:47]
	v_pk_fma_f32 v[44:45], v[40:41], v[40:41], v[44:45]
	v_and_b32_e32 v31, 0xffff0000, v42
	v_pk_fma_f32 v[74:75], v[72:73], v[72:73], v[74:75]
	v_add_f32_e32 v0, v44, v45
	v_lshlrev_b32_e32 v34, 16, v42
	v_pk_mul_f32 v[42:43], v[30:31], v[30:31]
	v_add_f32_e32 v0, v74, v0
	v_pk_fma_f32 v[42:43], v[34:35], v[34:35], v[42:43]
	v_add_f32_e32 v0, v75, v0
	v_add_f32_e32 v0, v42, v0
	v_add_f32_e32 v0, v43, v0
	v_add_f32_e32 v0, v70, v0
	v_add_f32_e32 v0, v71, v0
	ds_bpermute_b32 v42, v37, v0
	v_mov_b32_e32 v68, v49
	v_mov_b32_e32 v69, v50
	v_mov_b32_e32 v32, v11
	v_mov_b32_e32 v33, v12
	s_waitcnt lgkmcnt(0)
; __device__ __forceinline__ void phase_qkprep(bf16_t* proj, const float* gqk  , const float2* rope) {
;     ...
;         float ss = 0.f;
; #pragma unroll
;         for (int e = 0; e < 8; ++e) ss += x1[e] * x1[e] + x2[e] * x2[e];
;         ss += __shfl_xor(ss, 1); ss += __shfl_xor(ss, 2);
;         const float rstd = 1.0f / sqrtf(ss * (1.0f / 64.0f) + 1e-6f) * (which ? 1.0f : 0.125f * 1.4426950408889634f);
;         const float* gq = gqk + which * 64 + 8 * u;
;         const float2* cs = rope + (size_t)pos * 32 + 8 * u;
;         float o1[8], o2[8];
; #pragma unroll
;         for (int e = 0; e < 8; ++e) { const float y1 = x1[e] * rstd * gq[e], y2 = x2[e] * rstd * gq[32 + e]; const float2 t = cs[e]; o1[e] = y1 * t.x - y2 * t.y; o2[e] = y2 * t.x + y1 * t.y; }
;         *(u32x4*)p = pack8(o1); *(u32x4*)(p + 32) = pack8(o2);
	v_add_f32_e32 v0, v0, v42
	ds_bpermute_b32 v42, v38, v0
	v_mov_b32_e32 v28, v7
	v_mov_b32_e32 v29, v8
	v_mov_b32_e32 v22, v3
	v_mov_b32_e32 v23, v4
	s_waitcnt lgkmcnt(0)
	v_add_f32_e32 v0, v0, v42
	v_fmamk_f32 v0, v0, 0x3c800000, v195
	v_cmp_gt_f32_e32 vcc, s50, v0
	v_mul_f32_e32 v42, 0x4f800000, v0
	s_nop 0
	v_cndmask_b32_e32 v0, v0, v42, vcc
	v_sqrt_f32_e32 v42, v0
	s_nop 0
	v_add_u32_e32 v43, -1, v42
	v_fma_f32 v44, -v43, v42, v0
	v_cmp_ge_f32_e64 s[0:1], 0, v44
	v_add_u32_e32 v44, 1, v42
	s_nop 0
	v_cndmask_b32_e64 v43, v42, v43, s[0:1]
	v_fma_f32 v42, -v44, v42, v0
	v_cmp_lt_f32_e64 s[0:1], 0, v42
	s_nop 1
	v_cndmask_b32_e64 v42, v43, v44, s[0:1]
	v_mul_f32_e32 v43, 0x37800000, v42
	v_cndmask_b32_e32 v42, v42, v43, vcc
	v_cmp_class_f32_e32 vcc, v0, v232
	s_nop 1
	v_cndmask_b32_e32 v0, v42, v0, vcc
	v_div_scale_f32 v42, s[0:1], v0, v0, 1.0
	v_rcp_f32_e32 v43, v42
	s_nop 0
	v_fma_f32 v44, -v42, v43, 1.0
	v_fmac_f32_e32 v43, v44, v43
	v_div_scale_f32 v44, vcc, 1.0, v0, 1.0
	v_mul_f32_e32 v45, v44, v43
	v_fma_f32 v70, -v42, v45, v44
	v_fmac_f32_e32 v45, v70, v43
	v_fma_f32 v42, -v42, v45, v44
	v_div_fmas_f32 v42, v42, v43, v45
	v_div_fixup_f32 v0, v42, v0, 1.0
	v_mul_f32_e32 v0, v39, v0
	v_pk_mul_f32 v[40:41], v[0:1], v[40:41] op_sel_hi:[0,1]
	v_mov_b32_e32 v42, v56
	v_mov_b32_e32 v43, v65
	v_pk_mul_f32 v[40:41], v[42:43], v[40:41]
	v_pk_mul_f32 v[42:43], v[0:1], v[76:77] op_sel_hi:[0,1]
	v_mov_b32_e32 v65, v57
	v_pk_mul_f32 v[42:43], v[64:65], v[42:43]
	v_mov_b32_e32 v44, v48
	v_mov_b32_e32 v45, v51
	v_pk_mul_f32 v[44:45], v[44:45], v[42:43]
	v_mov_b32_e32 v57, v50
	v_mov_b32_e32 v65, v43
	v_mov_b32_e32 v50, v49
	v_mov_b32_e32 v43, v41
	v_pk_fma_f32 v[44:45], v[68:69], v[40:41], v[44:45]
	v_mov_b32_e32 v56, v48
	v_mov_b32_e32 v64, v40
	v_pk_mul_f32 v[40:41], v[50:51], v[42:43]
	v_pk_mul_f32 v[42:43], v[0:1], v[72:73] op_sel_hi:[0,1]
	v_mov_b32_e32 v48, v58
	v_mov_b32_e32 v49, v67
	v_pk_mul_f32 v[46:47], v[0:1], v[46:47] op_sel_hi:[0,1]
	v_mov_b32_e32 v67, v59
	v_pk_mul_f32 v[42:43], v[48:49], v[42:43]
	v_pk_mul_f32 v[46:47], v[66:67], v[46:47]
	v_mov_b32_e32 v48, v10
	v_mov_b32_e32 v49, v13
	v_pk_mul_f32 v[48:49], v[48:49], v[46:47]
	v_mov_b32_e32 v51, v47
	v_pk_fma_f32 v[32:33], v[32:33], v[42:43], v[48:49]
	v_mov_b32_e32 v49, v12
	v_mov_b32_e32 v12, v11
	v_mov_b32_e32 v47, v43
	v_mov_b32_e32 v48, v10
	v_pk_mul_f32 v[10:11], v[12:13], v[46:47]
	v_pk_mul_f32 v[12:13], v[0:1], v[34:35] op_sel_hi:[0,1]
	v_mov_b32_e32 v34, v52
	v_mov_b32_e32 v35, v61
	v_pk_mul_f32 v[30:31], v[0:1], v[30:31] op_sel_hi:[0,1]
	v_mov_b32_e32 v61, v53
	v_pk_mul_f32 v[12:13], v[34:35], v[12:13]
	v_pk_mul_f32 v[30:31], v[60:61], v[30:31]
	v_mov_b32_e32 v34, v6
	v_mov_b32_e32 v35, v9
	v_pk_mul_f32 v[34:35], v[34:35], v[30:31]
	v_mov_b32_e32 v43, v8
	v_pk_fma_f32 v[28:29], v[12:13], v[28:29], v[34:35]
	v_mov_b32_e32 v35, v31
	v_mov_b32_e32 v31, v13
	v_mov_b32_e32 v8, v7
	v_mov_b32_e32 v50, v42
	v_mov_b32_e32 v34, v6
	v_mov_b32_e32 v42, v12
	v_pk_mul_f32 v[6:7], v[30:31], v[8:9]
	v_pk_mul_f32 v[8:9], v[0:1], v[26:27] op_sel_hi:[0,1]
	v_mov_b32_e32 v12, v54
	v_mov_b32_e32 v13, v63
	v_pk_mul_f32 v[8:9], v[8:9], v[12:13]
	v_pk_mul_f32 v[12:13], v[0:1], v[24:25] op_sel_hi:[0,1]
	v_mov_b32_e32 v63, v55
	v_pk_mul_f32 v[12:13], v[12:13], v[62:63]
	v_mov_b32_e32 v24, v2
	v_mov_b32_e32 v25, v5
	v_pk_mul_f32 v[24:25], v[12:13], v[24:25]
	v_mov_b32_e32 v27, v4
	v_pk_fma_f32 v[22:23], v[8:9], v[22:23], v[24:25]
	v_mov_b32_e32 v25, v13
	v_mov_b32_e32 v13, v9
	v_mov_b32_e32 v4, v3
	v_mov_b32_e32 v24, v8
	v_mov_b32_e32 v26, v2
	v_pk_mul_f32 v[2:3], v[12:13], v[4:5]
	v_pk_fma_f32 v[40:41], v[56:57], v[64:65], v[40:41] neg_lo:[0,0,1] neg_hi:[0,0,1]
	v_pk_fma_f32 v[10:11], v[48:49], v[50:51], v[10:11] neg_lo:[0,0,1] neg_hi:[0,0,1]
	v_pk_fma_f32 v[6:7], v[34:35], v[42:43], v[6:7] neg_lo:[0,0,1] neg_hi:[0,0,1]
	v_pk_fma_f32 v[8:9], v[24:25], v[26:27], v[2:3] neg_lo:[0,0,1] neg_hi:[0,0,1]
	v_cvt_pk_bf16_f32 v2, v40, v41
	v_cvt_pk_bf16_f32 v3, v10, v11
	v_cvt_pk_bf16_f32 v4, v6, v7
	v_cvt_pk_bf16_f32 v5, v8, v9
	v_cmp_lt_i32_e32 vcc, s49, v36
	global_store_dwordx4 v[20:21], v[2:5], off
	s_or_b64 s[6:7], vcc, s[6:7]
	s_nop 0
	v_cvt_pk_bf16_f32 v2, v44, v45
	v_cvt_pk_bf16_f32 v3, v32, v33
	v_cvt_pk_bf16_f32 v4, v28, v29
	v_cvt_pk_bf16_f32 v5, v22, v23
	global_store_dwordx4 v[20:21], v[2:5], off offset:64
	s_waitcnt vmcnt(2)
	s_andn2_b64 exec, exec, s[6:7]
	s_cbranch_execnz .LBB0_309
	s_or_b64 exec, exec, s[6:7]
